# plus: transposed scan-output and state stores (4 dwordx2 / 4 ds_write_b64 instead of 16 shorts), commit address hoisted, scalar-base fast path for interior prefetch chunks
# speedup vs baseline: 1.0412x; 1.0080x over previous
; __device__ __forceinline__ u16 f2bf(float f) { return (u16)(pack2(f, 0.f) & 0xffffu); }
; __device__ __forceinline__ float bf2f(u16 h) { return __uint_as_float(((unsigned)h) << 16); }
; __device__ void dn_item(const Params& p, int l, int item, char* smem, int wv) {
;     ...
;       for (int n = 0; n < 4; ++n) {
;         const int jj = n * 16 + fr;
;         float lv[4];
; #pragma unroll
;         for (int j = 0; j < 4; ++j) {
;           int i = i0 + j;
;           float e = (i >= jj) ? __expf(gi[j] - gj[n]) : 0.f;
;           lv[j] = (i > jj) ? bi[j] * kk4[n][j] * e : 0.f;
;           Ib[i * 72 + jj] = f2bf(qk[n][j] * e);
;           rhs[n][j] = bi[j] * (bf2f(vraw[n][j]) - eg[j] * rhs[n][j]);
;         }
;         *(float4*)(LfT + jj * 68 + i0) = make_float4(lv[0], lv[1], lv[2], lv[3]);
;       }
;     }
;     lds_barrier();
; #pragma unroll
;     for (int n = 0; n < 4; ++n)
; #pragma unroll
;       for (int j = 0; j < 4; ++j) X[(16 * wave + fq * 4 + j) * XS + n * 16 + fr] = rhs[n][j];
;     {
;       const int c = lane & 15;
;       const float* ld = LfT + (16 * wave) * 68 + 16 * wave;
;       float x[16];
; #pragma unroll
;       for (int i = 0; i < 16; ++i) x[i] = (i == c) ? 1.f : 0.f;
.LBB0_334:
	s_movk_i32 s14, 0xc0
	s_or_b64 exec, exec, s[2:3]
	v_ashrrev_i32_e32 v41, 2, v78
	v_readlane_b32 s6, v253, 40
	v_sub_u32_e32 v0, 63, v41
	v_readlane_b32 s7, v253, 41
	v_ashrrev_i32_e32 v38, 6, v78
	v_lshrrev_b32_e32 v39, 4, v31
	v_cndmask_b32_e64 v42, v0, v41, s[6:7]
	v_lshlrev_b32_e32 v0, 4, v78
	v_and_b32_e32 v40, 15, v78
	v_and_b32_e32 v43, 48, v0
	v_lshlrev_b32_e32 v0, 2, v39
	v_readlane_b32 s3, v254, 2
	v_lshlrev_b32_e32 v48, 4, v38
	v_or_b32_e32 v49, v0, v48
	v_add_u32_e32 v47, s3, v0
	v_or_b32_e32 v0, v48, v40
	v_and_b32_e32 v48, 48, v31
	s_add_i32 s0, 16, 0x13040
	v_add_u32_e32 v80, 16, v48
	s_movk_i32 s4, 0x90
	v_lshl_add_u32 v186, v43, 2, s0
	s_waitcnt vmcnt(0)
	v_mad_u64_u32 v[82:83], s[0:1], v0, s4, v[80:81]
	s_movk_i32 s0, 0x1100
	v_and_b32_e32 v0, 48, v78
	v_mul_lo_u32 v51, v38, s0
	v_readlane_b32 s0, v253, 58
	v_add_u32_e32 v83, 16, v0
	v_lshlrev_b32_e32 v0, 1, v40
	v_readlane_b32 s1, v253, 59
	v_lshl_add_u32 v32, v43, 1, 16
	v_lshlrev_b32_e32 v46, 2, v40
	v_lshl_add_u64 v[84:85], s[0:1], 0, v[0:1]
	v_cmp_eq_u32_e64 s[0:1], 0, v31
	v_and_b32_e32 v52, 0xffffffc0, v78
	v_lshlrev_b32_e32 v44, 2, v31
	v_writelane_b32 v254, s0, 38
	v_add_u32_e32 v189, 16, v46
	v_add3_u32 v191, 16, v51, v52
	v_writelane_b32 v254, s1, 39
	v_cmp_gt_u32_e64 s[0:1], 2, v31
	v_and_b32_e32 v51, -16, v41
	v_add_u32_e32 v193, v189, v52
	v_writelane_b32 v254, s0, 40
	v_add_u32_e32 v52, 16, v44
	v_mul_u32_u24_e32 v53, 0x8c, v31
	v_writelane_b32 v254, s1, 41
	v_cndmask_b32_e64 v196, v33, v30, s[0:1]
	v_cmp_gt_u32_e64 s[0:1], 4, v31
	v_lshlrev_b32_e32 v54, 1, v51
	v_cmp_ne_u32_e32 vcc, 0, v31
	v_writelane_b32 v254, s0, 42
	v_cmp_gt_u32_e64 s[46:47], 16, v31
	v_add3_u32 v194, v52, v53, v54
	v_writelane_b32 v254, s1, 43
	v_cndmask_b32_e64 v197, v34, v30, s[0:1]
	v_cmp_gt_u32_e64 s[0:1], 8, v31
	v_mov_b32_e32 v34, 0x1b00
	v_mad_u32_u24 v204, v40, s4, v34
	v_writelane_b32 v254, s0, 44
	v_or_b32_e32 v34, 1, v49
	v_subbrev_co_u32_e32 v53, vcc, 0, v78, vcc
	v_writelane_b32 v254, s1, 45
	v_cndmask_b32_e64 v198, v35, v30, s[0:1]
	v_cmp_gt_u32_e64 s[0:1], 32, v31
	v_or_b32_e32 v35, 3, v49
	v_cndmask_b32_e64 v199, v36, v30, s[46:47]
	v_writelane_b32 v254, s0, 46
	v_or_b32_e32 v36, 2, v49
	v_cmp_eq_u32_e32 vcc, 0, v40
	v_writelane_b32 v254, s1, 47
	v_cndmask_b32_e64 v200, v37, v30, s[0:1]
	s_movk_i32 s0, 0x190
	v_mad_u64_u32 v[86:87], s[0:1], v41, s0, v[32:33]
	v_mad_u64_u32 v[88:89], s[0:1], v42, s4, v[32:33]
	v_cmp_gt_i32_e64 s[0:1], v49, v40
	v_cndmask_b32_e64 v218, 0, 1.0, vcc
	v_cmp_eq_u32_e32 vcc, 1, v40
	v_writelane_b32 v254, s0, 48
	v_or_b32_e32 v31, 16, v40
	v_cndmask_b32_e64 v219, 0, 1.0, vcc
	v_writelane_b32 v254, s1, 49
	v_cmp_lt_i32_e64 s[0:1], v34, v40
	v_cmp_eq_u32_e32 vcc, 2, v40
	v_lshlrev_b32_e32 v38, 10, v38
	v_writelane_b32 v254, s0, 50
	v_cndmask_b32_e64 v220, 0, 1.0, vcc
	v_cmp_eq_u32_e32 vcc, 3, v40
	v_writelane_b32 v254, s1, 51
	v_cmp_lt_i32_e64 s[0:1], v35, v40
	v_cndmask_b32_e64 v221, 0, 1.0, vcc
	v_cmp_eq_u32_e32 vcc, 4, v40
	v_writelane_b32 v254, s0, 52
	v_mov_b32_e32 v32, 0x900
	v_cndmask_b32_e64 v222, 0, 1.0, vcc
	v_writelane_b32 v254, s1, 53
	v_cmp_lt_i32_e64 s[0:1], v36, v40
	v_cmp_eq_u32_e32 vcc, 5, v40
	v_mov_b32_e32 v33, 0x1200
	v_writelane_b32 v254, s0, 54
	v_cndmask_b32_e64 v223, 0, 1.0, vcc
	v_cmp_eq_u32_e32 vcc, 6, v40
	v_writelane_b32 v254, s1, 55
	v_cmp_gt_i32_e64 s[0:1], v35, v40
	v_cndmask_b32_e64 v224, 0, 1.0, vcc
	v_cmp_eq_u32_e32 vcc, 7, v40
	v_writelane_b32 v254, s0, 56
	v_sub_u32_e32 v190, v189, v0
	v_cndmask_b32_e64 v225, 0, 1.0, vcc
	v_writelane_b32 v254, s1, 57
	v_cmp_gt_i32_e64 s[0:1], v36, v40
	v_cmp_eq_u32_e32 vcc, 8, v40
	v_add3_u32 v192, s3, v38, v46
	v_writelane_b32 v254, s0, 58
	v_cndmask_b32_e64 v226, 0, 1.0, vcc
	v_cmp_eq_u32_e32 vcc, 9, v40
	v_writelane_b32 v254, s1, 59
	v_cmp_gt_i32_e64 s[0:1], v49, v31
	v_cndmask_b32_e64 v227, 0, 1.0, vcc
	v_cmp_eq_u32_e32 vcc, 10, v40
	v_writelane_b32 v254, s0, 60
	v_lshlrev_b32_e32 v38, 6, v40
	v_cndmask_b32_e64 v228, 0, 1.0, vcc
	v_writelane_b32 v254, s1, 61
	v_cmp_lt_i32_e64 s[0:1], v34, v31
	v_cmp_eq_u32_e32 vcc, 11, v40
	v_mul_u32_u24_e32 v87, 0x90, v40
	v_writelane_b32 v254, s0, 62
	v_cndmask_b32_e64 v229, 0, 1.0, vcc
	v_cmp_eq_u32_e32 vcc, 12, v40
	v_writelane_b32 v254, s1, 63
	v_cmp_lt_i32_e64 s[0:1], v35, v31
	v_cndmask_b32_e64 v230, 0, 1.0, vcc
	v_cmp_eq_u32_e32 vcc, 13, v40
	v_writelane_b32 v255, s0, 0
	v_mad_u32_u24 v89, v40, s4, v32
	v_cndmask_b32_e64 v231, 0, 1.0, vcc
	v_writelane_b32 v255, s1, 1
	v_cmp_lt_i32_e64 s[0:1], v36, v31
; __device__ void dn_item(const Params& p, int l, int item, char* smem, int wv) {
;     ...
;   auto commit = [&]() {
;     int tl = tid;
;     asm volatile("" : "+v"(tl));
;     const int rr = tl / 24, seg = tl - rr * 24, part = seg >> 3, s8 = seg & 7;
; #pragma unroll
;     for (int q = 0; q < 7; ++q) {
;       int r = rr + 10 * q;
;       if (tl < 240 && r < 68) *(uint4*)(R0 + r * RS + part * 64 + s8 * 8) = pre[q];
	v_cmp_eq_u32_e32 vcc, 14, v40
	v_or_b32_e32 v32, 32, v40
	v_writelane_b32 v255, s0, 2
	v_mad_u32_u24 v203, v40, s4, v33
	v_or_b32_e32 v33, 48, v40
	v_writelane_b32 v255, s1, 3
	v_cmp_gt_i32_e64 s[0:1], v35, v31
	v_add_u32_e32 v217, 16, v0
	v_cmp_lt_i32_e64 s[50:51], v49, v40
	v_mul_u32_u24_e32 v0, 0x110, v40
	v_writelane_b32 v255, s0, 4
	v_cndmask_b32_e64 v232, 0, 1.0, vcc
	v_cmp_eq_u32_e32 vcc, 15, v40
	v_or_b32_e32 v40, 15, v41
	v_sub_u32_e32 v41, 63, v49
	v_writelane_b32 v255, s1, 5
	v_cmp_gt_i32_e64 s[0:1], v36, v31
	v_cndmask_b32_e64 v235, v41, v49, s[6:7]
	v_sub_u32_e32 v41, 63, v34
	s_add_i32 s2, 16, 0x11e40
	v_lshlrev_b32_e32 v48, 2, v49
	s_add_i32 s3, 16, 0x11f40
	v_lshlrev_b32_e32 v37, 2, v36
	v_writelane_b32 v255, s0, 6
	v_cmp_lt_i32_e64 s[82:83], v34, v32
	v_cmp_lt_i32_e64 s[96:97], v34, v33
	s_movk_i32 s15, 0x110
	v_cndmask_b32_e64 v236, v41, v34, s[6:7]
	v_sub_u32_e32 v34, 63, v36
	v_lshl_add_u32 v185, v42, 2, s2
	v_lshl_add_u32 v45, v42, 1, 16
	v_add_u32_e32 v50, 16, v48
	v_add_u32_e32 v201, s2, v44
	v_add_u32_e32 v202, s3, v44
	v_mul_u32_u24_e32 v30, 0x90, v43
	v_add_u32_e32 v205, s2, v48
	v_add_u32_e32 v206, s3, v48
	v_add_u32_e32 v207, s2, v46
	v_lshl_add_u32 v208, v31, 2, s2
	v_lshl_add_u32 v209, v32, 2, s2
	v_add_u32_e32 v210, s2, v37
	v_add_u32_e32 v211, s3, v37
	v_lshl_add_u32 v212, v35, 2, s2
	v_lshl_add_u32 v213, v33, 2, s2
	v_mul_lo_u32 v214, v49, s4
	v_mul_lo_u32 v215, v36, s4
	v_mul_lo_u32 v216, v35, s4
	v_cmp_lt_i32_e64 s[64:65], v49, v31
	v_writelane_b32 v255, s1, 7
	v_cmp_lt_i32_e64 s[78:79], v49, v32
	v_cmp_gt_i32_e64 s[80:81], v49, v32
	v_cmp_lt_i32_e64 s[84:85], v35, v32
	v_cmp_lt_i32_e64 s[86:87], v36, v32
	v_cmp_gt_i32_e64 s[88:89], v35, v32
	v_cmp_gt_i32_e64 s[90:91], v36, v32
	v_cmp_lt_i32_e64 s[92:93], v49, v33
	v_cmp_gt_i32_e64 s[48:49], v49, v33
	v_cmp_lt_i32_e64 s[98:99], v35, v33
	v_cmp_lt_i32_e64 s[0:1], v36, v33
	v_cmp_gt_i32_e64 s[2:3], v35, v33
	v_cmp_gt_i32_e64 s[4:5], v36, v33
	v_mul_lo_u32 v31, v49, s15
	v_mul_lo_u32 v32, v36, s15
	v_mul_lo_u32 v33, v35, s15
	v_mul_u32_u24_e32 v234, 0x110, v39
	v_mul_u32_u24_e32 v37, 0x440, v39
	v_mul_lo_u32 v39, v51, s15
	v_mul_lo_u32 v40, v40, s15
	v_cndmask_b32_e64 v237, v34, v36, s[6:7]
	v_sub_u32_e32 v34, 63, v35
	v_mov_b32_e32 v90, 0
	v_xor_b32_e32 v187, 4, v44
	v_xor_b32_e32 v188, 8, v44
	v_lshlrev_b32_e32 v195, 2, v53
	v_cndmask_b32_e64 v233, 0, 1.0, vcc
	v_cndmask_b32_e64 v238, v34, v35, s[6:7]
	s_mov_b32 s42, -4
	v_add_u32_e32 v239, v45, v30
	v_add_u32_e32 v240, v50, v0
	v_add_u32_e32 v241, v189, v31
	v_add_u32_e32 v242, v189, v32
	v_add_u32_e32 v243, v189, v33
	v_add_u32_e32 v244, v47, v38
	v_add_u32_e32 v245, v193, v37
	v_add_u32_e32 v246, v52, v39
	v_add_u32_e32 v247, v52, v40
	v_mov_b32_e32 v91, v90
	v_mov_b32_e32 v92, v90
	v_mov_b32_e32 v93, v90
	v_mov_b32_e32 v94, v90
	v_mov_b32_e32 v95, v90
	v_mov_b32_e32 v96, v90
	v_mov_b32_e32 v97, v90
	v_mov_b32_e32 v98, v90
	v_mov_b32_e32 v99, v90
	v_mov_b32_e32 v100, v90
	v_mov_b32_e32 v101, v90
	v_mov_b32_e32 v102, v90
	v_mov_b32_e32 v103, v90
	v_mov_b32_e32 v104, v90
	v_mov_b32_e32 v105, v90
	v_lshrrev_b32_e32 v30, 3, v78
	v_and_b32_e32 v31, 7, v78
	v_lshlrev_b32_e32 v32, 4, v31
	v_mul_u32_u24_e32 v187, 0x320, v30
	v_add3_u32 v187, v187, v32, 16
	v_lshlrev_b32_e32 v188, 5, v31
	v_add_u32_e32 v188, 0x13050, v188
	v_lshlrev_b32_e32 v33, 1, v30
	v_sub_u32_e32 v34, 63, v33
	v_readlane_b32 s6, v253, 40
	v_readlane_b32 s7, v253, 41
	v_add_u32_e32 v35, 1, v33
	v_add_u32_e32 v36, -1, v34
	v_cndmask_b32_e64 v33, v34, v33, s[6:7]
	v_cndmask_b32_e64 v35, v36, v35, s[6:7]
	v_cndmask_b32_e64 v36, v35, v33, s[6:7]
	v_mul_u32_u24_e32 v195, 0x90, v33
	v_mul_u32_u24_e32 v196, 0x90, v35
	v_add3_u32 v195, v195, v32, 16
	v_add3_u32 v196, v196, v32, 16
	v_mul_u32_u24_e32 v197, 0x480, v31
	v_lshl_add_u32 v197, v36, 1, v197
	v_add_u32_e32 v197, 0xd650, v197
	v_lshlrev_b32_e32 v198, 2, v33
	v_lshlrev_b32_e32 v199, 2, v35
	v_add_u32_e32 v198, 0x11e50, v198
	v_add_u32_e32 v199, 0x11e50, v199
	s_mov_b32 s6, 0x2aaaaaab
	v_mul_hi_i32 v30, v78, s6
	v_lshrrev_b32_e32 v31, 31, v30
	v_ashrrev_i32_e32 v30, 2, v30
	v_add_u32_e32 v30, v30, v31
	s_movk_i32 s6, 0xffe8
	v_mul_lo_u32 v31, v30, s6
	v_add_lshl_u32 v31, v31, v78, 3
	v_lshlrev_b32_e32 v32, 3, v78
	s_movk_i32 s6, 0x190
	v_and_b32_e32 v31, 0xffffffc0, v31
	v_and_b32_e32 v32, 56, v32
	v_mul_lo_u32 v33, v30, s6
	v_lshlrev_b32_e32 v30, 1, v31
	v_lshlrev_b32_e32 v31, 1, v32
	v_add_u32_e32 v32, 16, v33
	v_add3_u32 v200, v32, v30, v31
	s_waitcnt lgkmcnt(0)
	s_barrier
	s_branch .LBB0_339

; __device__ __forceinline__ u16 f2bf(float f) { return (u16)(pack2(f, 0.f) & 0xffffu); }
; __device__ void dn_item(const Params& p, int l, int item, char* smem, int wv) {
;     ...
;         for (int kb2 = 0; kb2 < 2; ++kb2) {
;           const int k0 = kb2 * 3, nk = kb2 ? 2 : 3;
;           uint4 rv[3][2];
;           float4 wv4[3][4];
; #pragma unroll
;           for (int kq = 0; kq < 3; ++kq) {
;             if (kq < nk) {
;               const int kk = k0 + kq;
;               const u16* rr = R0 + (ti + kk) * RS + part * 64 + dc * 16;
;               rv[kq][0] = *(const uint4*)rr;
;               rv[kq][1] = *(const uint4*)(rr + 8);
;               const float* wp = cw + kk * 192 + part * 64 + dc * 16;
; #pragma unroll
;               for (int e4 = 0; e4 < 4; ++e4) wv4[kq][e4] = *(const float4*)(wp + e4 * 4);
;             }
;           }
;           __builtin_amdgcn_sched_barrier(0);
; #pragma unroll
;           for (int kq = 0; kq < 3; ++kq) {
;             if (kq < nk) {
;               unsigned rw[8] = {rv[kq][0].x, rv[kq][0].y, rv[kq][0].z, rv[kq][0].w, rv[kq][1].x, rv[kq][1].y, rv[kq][1].z, rv[kq][1].w};
; #pragma unroll
;               for (int e4 = 0; e4 < 4; ++e4) {
;                 float4 w = wv4[kq][e4];
;                 acc[e4 * 4 + 0] += w.x * __uint_as_float(rw[e4 * 2] << 16);
;                 acc[e4 * 4 + 1] += w.y * __uint_as_float(rw[e4 * 2] & 0xffff0000u);
;                 acc[e4 * 4 + 2] += w.z * __uint_as_float(rw[e4 * 2 + 1] << 16);
;                 acc[e4 * 4 + 3] += w.w * __uint_as_float(rw[e4 * 2 + 1] & 0xffff0000u);
;               }
;             }
;           }
;           __builtin_amdgcn_sched_barrier(0);
;     ...
;         u16* dst = (part == 0 ? Qb : (part == 1 ? Kb : Vb)) + ip * 72 + dc * 16;
;         *(uint4*)dst = make_uint4(pack2(acc[0], acc[1]), pack2(acc[2], acc[3]), pack2(acc[4], acc[5]), pack2(acc[6], acc[7]));
;         *(uint4*)(dst + 8) = make_uint4(pack2(acc[8], acc[9]), pack2(acc[10], acc[11]), pack2(acc[12], acc[13]), pack2(acc[14], acc[15]));
;         if (part == 1) {
; #pragma unroll
;           for (int e = 0; e < 16; ++e) KdT[(dc * 16 + e) * 72 + ip] = f2bf(acc[e] * ekd);
.Lb_kdt_st:
	ds_write_b32 v197, v164 offset:0
	ds_write_b32 v197, v165 offset:144
	ds_write_b32 v197, v166 offset:288
	ds_write_b32 v197, v167 offset:432
	ds_write_b32 v197, v168 offset:576
	ds_write_b32 v197, v169 offset:720
	ds_write_b32 v197, v170 offset:864
	ds_write_b32 v197, v171 offset:1008
	v_cvt_pk_bf16_f32 v172, v144, v145
	v_cvt_pk_bf16_f32 v173, v146, v147
	v_cvt_pk_bf16_f32 v174, v148, v149
	v_cvt_pk_bf16_f32 v175, v150, v151
	ds_write_b128 v195, v[172:175] offset:27200
	v_cvt_pk_bf16_f32 v136, v152, v153
	v_cvt_pk_bf16_f32 v137, v154, v155
	v_cvt_pk_bf16_f32 v138, v156, v157
	v_cvt_pk_bf16_f32 v139, v158, v159
	ds_write_b128 v196, v[136:139] offset:27200
	s_waitcnt lgkmcnt(10)
	v_lshlrev_b32_e32 v122, 16, v30
	v_and_b32_e32 v123, 0xffff0000, v30
	v_lshlrev_b32_e32 v160, 16, v31
	v_and_b32_e32 v161, 0xffff0000, v31
	v_lshlrev_b32_e32 v124, 16, v34
	v_and_b32_e32 v125, 0xffff0000, v34
	v_lshlrev_b32_e32 v162, 16, v35
	v_and_b32_e32 v163, 0xffff0000, v35
	v_lshlrev_b32_e32 v126, 16, v38
	v_and_b32_e32 v127, 0xffff0000, v38
	v_lshlrev_b32_e32 v164, 16, v39
	v_and_b32_e32 v165, 0xffff0000, v39
	v_lshlrev_b32_e32 v128, 16, v42
	v_and_b32_e32 v129, 0xffff0000, v42
	v_lshlrev_b32_e32 v166, 16, v43
	v_and_b32_e32 v167, 0xffff0000, v43
	v_lshlrev_b32_e32 v140, 16, v46
	v_and_b32_e32 v141, 0xffff0000, v46
	v_lshlrev_b32_e32 v168, 16, v47
	v_and_b32_e32 v169, 0xffff0000, v47
	v_lshlrev_b32_e32 v142, 16, v50
	v_and_b32_e32 v143, 0xffff0000, v50
	v_lshlrev_b32_e32 v170, 16, v51
	v_and_b32_e32 v171, 0xffff0000, v51
	v_pk_fma_f32 v[144:145], v[54:55], v[122:123], 0 op_sel_hi:[1,1,0]
	v_pk_fma_f32 v[152:153], v[54:55], v[124:125], 0 op_sel_hi:[1,1,0]
	v_pk_fma_f32 v[146:147], v[56:57], v[160:161], 0 op_sel_hi:[1,1,0]
	v_pk_fma_f32 v[154:155], v[56:57], v[162:163], 0 op_sel_hi:[1,1,0]
	v_pk_fma_f32 v[144:145], v[62:63], v[124:125], v[144:145]
	v_pk_fma_f32 v[152:153], v[62:63], v[126:127], v[152:153]
	v_pk_fma_f32 v[146:147], v[64:65], v[162:163], v[146:147]
	v_pk_fma_f32 v[154:155], v[64:65], v[164:165], v[154:155]
	v_pk_fma_f32 v[144:145], v[70:71], v[126:127], v[144:145]
	v_pk_fma_f32 v[152:153], v[70:71], v[128:129], v[152:153]
	v_pk_fma_f32 v[146:147], v[72:73], v[164:165], v[146:147]
	v_pk_fma_f32 v[154:155], v[72:73], v[166:167], v[154:155]
	v_pk_fma_f32 v[144:145], v[106:107], v[128:129], v[144:145]
	v_pk_fma_f32 v[152:153], v[106:107], v[140:141], v[152:153]
	v_pk_fma_f32 v[146:147], v[108:109], v[166:167], v[146:147]
	v_pk_fma_f32 v[154:155], v[108:109], v[168:169], v[154:155]
	v_pk_fma_f32 v[144:145], v[114:115], v[140:141], v[144:145]
	v_pk_fma_f32 v[152:153], v[114:115], v[142:143], v[152:153]
	v_pk_fma_f32 v[146:147], v[116:117], v[168:169], v[146:147]
	v_pk_fma_f32 v[154:155], v[116:117], v[170:171], v[154:155]
	v_lshlrev_b32_e32 v122, 16, v32
	v_and_b32_e32 v123, 0xffff0000, v32
	v_lshlrev_b32_e32 v160, 16, v33
	v_and_b32_e32 v161, 0xffff0000, v33
	v_lshlrev_b32_e32 v124, 16, v36
	v_and_b32_e32 v125, 0xffff0000, v36
	v_lshlrev_b32_e32 v162, 16, v37
	v_and_b32_e32 v163, 0xffff0000, v37
	v_lshlrev_b32_e32 v126, 16, v40
	v_and_b32_e32 v127, 0xffff0000, v40
	v_lshlrev_b32_e32 v164, 16, v41
	v_and_b32_e32 v165, 0xffff0000, v41
	v_lshlrev_b32_e32 v128, 16, v44
	v_and_b32_e32 v129, 0xffff0000, v44
	v_lshlrev_b32_e32 v166, 16, v45
	v_and_b32_e32 v167, 0xffff0000, v45
	v_lshlrev_b32_e32 v140, 16, v48
	v_and_b32_e32 v141, 0xffff0000, v48
	v_lshlrev_b32_e32 v168, 16, v49
	v_and_b32_e32 v169, 0xffff0000, v49
	v_lshlrev_b32_e32 v142, 16, v52
	v_and_b32_e32 v143, 0xffff0000, v52
	v_lshlrev_b32_e32 v170, 16, v53
	v_and_b32_e32 v171, 0xffff0000, v53
	v_pk_fma_f32 v[148:149], v[58:59], v[122:123], 0 op_sel_hi:[1,1,0]
	v_pk_fma_f32 v[156:157], v[58:59], v[124:125], 0 op_sel_hi:[1,1,0]
	v_pk_fma_f32 v[150:151], v[60:61], v[160:161], 0 op_sel_hi:[1,1,0]
	v_pk_fma_f32 v[158:159], v[60:61], v[162:163], 0 op_sel_hi:[1,1,0]
	v_pk_fma_f32 v[148:149], v[66:67], v[124:125], v[148:149]
	v_pk_fma_f32 v[156:157], v[66:67], v[126:127], v[156:157]
	v_pk_fma_f32 v[150:151], v[68:69], v[162:163], v[150:151]
	v_pk_fma_f32 v[158:159], v[68:69], v[164:165], v[158:159]
	v_pk_fma_f32 v[148:149], v[74:75], v[126:127], v[148:149]
	v_pk_fma_f32 v[156:157], v[74:75], v[128:129], v[156:157]
	v_pk_fma_f32 v[150:151], v[76:77], v[164:165], v[150:151]
	v_pk_fma_f32 v[158:159], v[76:77], v[166:167], v[158:159]
	v_pk_fma_f32 v[148:149], v[110:111], v[128:129], v[148:149]
	v_pk_fma_f32 v[156:157], v[110:111], v[140:141], v[156:157]
	v_pk_fma_f32 v[150:151], v[112:113], v[166:167], v[150:151]
	v_pk_fma_f32 v[158:159], v[112:113], v[168:169], v[158:159]
	v_pk_fma_f32 v[148:149], v[118:119], v[140:141], v[148:149]
	v_pk_fma_f32 v[156:157], v[118:119], v[142:143], v[156:157]
	v_pk_fma_f32 v[150:151], v[120:121], v[168:169], v[150:151]
	v_pk_fma_f32 v[158:159], v[120:121], v[170:171], v[158:159]
	v_pk_mul_f32 v[160:161], v[144:145], v[176:177] op_sel_hi:[1,0]
	v_pk_mul_f32 v[162:163], v[146:147], v[176:177] op_sel_hi:[1,0]
	v_pk_mul_f32 v[164:165], v[148:149], v[176:177] op_sel_hi:[1,0]
	v_pk_mul_f32 v[166:167], v[150:151], v[176:177] op_sel_hi:[1,0]
	v_pk_mul_f32 v[168:169], v[152:153], v[176:177] op_sel_hi:[1,0]
	v_pk_mul_f32 v[170:171], v[154:155], v[176:177] op_sel_hi:[1,0]
	v_pk_mul_f32 v[172:173], v[156:157], v[176:177] op_sel_hi:[1,0]
	v_pk_mul_f32 v[174:175], v[158:159], v[176:177] op_sel_hi:[1,0]
	v_exp_f32_e32 v160, v160
	v_exp_f32_e32 v161, v161
	v_exp_f32_e32 v162, v162
	v_exp_f32_e32 v163, v163
	v_exp_f32_e32 v164, v164
; __device__ void dn_item(const Params& p, int l, int item, char* smem, int wv) {
;     ...
;   auto prefetch = [&](int step) {
;     size_t gbase; int tb, Ls;
;     chunk_info(step, gbase, tb, Ls);
;     int tl = tid;
;     asm volatile("" : "+v"(tl));
;     const int rr = tl / 24, seg = tl - rr * 24, part = seg >> 3, s8 = seg & 7;
;     const u16* src = P + (gbase + tb - 2 + rr) * PS + C_QB + part * 384 + h * 64 + s8 * 8;
; #pragma unroll
;     for (int q = 0; q < 7; ++q) {
;       int r = rr + 10 * q;
;       int t = tb - 2 + r;
;       uint4 val = make_uint4(0, 0, 0, 0);
;       if (tl < 240 && r < 68 && t >= 0 && t < Ls) val = *(const uint4*)(src + (size_t)(10 * q) * PS);
;       pre[q] = val;
	v_exp_f32_e32 v165, v165
	v_exp_f32_e32 v166, v166
	v_exp_f32_e32 v167, v167
	v_exp_f32_e32 v168, v168
	v_exp_f32_e32 v169, v169
	v_exp_f32_e32 v170, v170
	v_exp_f32_e32 v171, v171
	v_exp_f32_e32 v172, v172
	v_exp_f32_e32 v173, v173
	v_exp_f32_e32 v174, v174
	v_exp_f32_e32 v175, v175
	v_pk_add_f32 v[160:161], v[160:161], v[180:181] op_sel_hi:[1,0]
	v_pk_add_f32 v[162:163], v[162:163], v[180:181] op_sel_hi:[1,0]
	v_pk_add_f32 v[164:165], v[164:165], v[180:181] op_sel_hi:[1,0]
	v_pk_add_f32 v[166:167], v[166:167], v[180:181] op_sel_hi:[1,0]
	v_pk_add_f32 v[168:169], v[168:169], v[180:181] op_sel_hi:[1,0]
	v_pk_add_f32 v[170:171], v[170:171], v[180:181] op_sel_hi:[1,0]
	v_pk_add_f32 v[172:173], v[172:173], v[180:181] op_sel_hi:[1,0]
	v_pk_add_f32 v[174:175], v[174:175], v[180:181] op_sel_hi:[1,0]
	v_rcp_f32_e32 v160, v160
	v_rcp_f32_e32 v161, v161
	v_rcp_f32_e32 v162, v162
	v_rcp_f32_e32 v163, v163
	v_rcp_f32_e32 v164, v164
	v_rcp_f32_e32 v165, v165
	v_rcp_f32_e32 v166, v166
	v_rcp_f32_e32 v167, v167
	v_rcp_f32_e32 v168, v168
	v_rcp_f32_e32 v169, v169
	v_rcp_f32_e32 v170, v170
	v_rcp_f32_e32 v171, v171
	v_rcp_f32_e32 v172, v172
	v_rcp_f32_e32 v173, v173
	v_rcp_f32_e32 v174, v174
	v_rcp_f32_e32 v175, v175
	s_nop 0
	v_pk_mul_f32 v[144:145], v[144:145], v[160:161]
	v_pk_mul_f32 v[146:147], v[146:147], v[162:163]
	v_pk_mul_f32 v[148:149], v[148:149], v[164:165]
	v_pk_mul_f32 v[150:151], v[150:151], v[166:167]
	v_pk_mul_f32 v[152:153], v[152:153], v[168:169]
	v_pk_mul_f32 v[154:155], v[154:155], v[170:171]
	v_pk_mul_f32 v[156:157], v[156:157], v[172:173]
	v_pk_mul_f32 v[158:159], v[158:159], v[174:175]
	v_cvt_pk_bf16_f32 v172, v144, v145
	v_cvt_pk_bf16_f32 v173, v146, v147
	v_cvt_pk_bf16_f32 v174, v148, v149
	v_cvt_pk_bf16_f32 v175, v150, v151
	ds_write_b128 v195, v[172:175] offset:36416
	v_cvt_pk_bf16_f32 v136, v152, v153
	v_cvt_pk_bf16_f32 v137, v154, v155
	v_cvt_pk_bf16_f32 v138, v156, v157
	v_cvt_pk_bf16_f32 v139, v158, v159
	ds_write_b128 v196, v[136:139] offset:36416
	s_cmp_lg_u32 s42, 63
	s_cselect_b64 s[38:39], -1, 0
	s_cmp_eq_u32 s42, 63
	s_waitcnt lgkmcnt(0)
	s_barrier
	s_cbranch_scc1 .LBB0_357
	s_add_i32 s6, s42, 5
	s_add_i32 s7, s42, 1
	s_cmp_lt_u32 s43, 3
	s_movk_i32 s36, 0x1000
	s_cselect_b32 s77, 0x100, s36
	v_readlane_b32 s36, v253, 51
	s_cselect_b32 s40, s6, s7
	v_readlane_b32 s7, v253, 44
	v_readlane_b32 s37, v253, 52
	s_cselect_b32 s6, 3, 63
	s_cselect_b32 s37, s7, s37
	v_readlane_b32 s7, v253, 43
	s_cselect_b32 s36, s7, s36
	s_sub_i32 s41, s6, s40
	v_readlane_b32 s6, v253, 40
	v_readlane_b32 s7, v253, 41
	s_and_b64 s[6:7], s[6:7], exec
	s_cselect_b32 s6, s40, s41
	s_lshl_b32 s76, s6, 6
	s_waitcnt vmcnt(0)
	s_lshr_b32 s40, s77, 6
	s_add_i32 s40, s40, -2
	s_lshr_b32 s41, s76, 6
	s_cmp_eq_u32 s41, 0
	s_cbranch_scc1 .Lpf_edge
	s_cmp_gt_u32 s41, s40
	s_cbranch_scc1 .Lpf_edge
	s_add_i32 s6, s36, s76
	s_add_i32 s6, s6, -2
	s_mul_hi_i32 s41, s6, s71
	s_mul_i32 s40, s6, s71
	s_add_u32 s40, s40, s18
	s_addc_u32 s41, s41, s19
	v_readlane_b32 s6, v253, 56
	s_lshl_b32 s6, s6, 1
	s_add_u32 s40, s40, s6
	s_addc_u32 s41, s41, 0
	s_mov_b32 s6, 0x2aaaaaab
	v_mul_hi_i32 v0, v78, s6
	v_lshrrev_b32_e32 v26, 31, v0
	v_ashrrev_i32_e32 v0, 2, v0
	v_add_u32_e32 v0, v0, v26
	v_mul_u32_u24_e32 v26, 24, v0
	v_sub_u32_e32 v26, v78, v26
	v_lshrrev_b32_e32 v27, 3, v26
	v_and_b32_e32 v26, 7, v26
	v_mul_u32_u24_e32 v27, 0x300, v27
	v_lshl_add_u32 v26, v26, 4, v27
	v_mad_u32_u24 v26, v0, s71, v26
	s_movk_i32 s6, 0xf0
	v_cmp_gt_i32_e32 vcc, s6, v78
	s_and_saveexec_b64 s[6:7], vcc
	global_load_dwordx4 v[2:5], v26, s[40:41] offset:1536
	v_add_u32_e32 v27, 0x10400, v26
	global_load_dwordx4 v[6:9], v27, s[40:41] offset:1536
	v_add_u32_e32 v27, 0x20800, v26
	global_load_dwordx4 v[10:13], v27, s[40:41] offset:1536
	v_add_u32_e32 v27, 0x30c00, v26
	global_load_dwordx4 v[14:17], v27, s[40:41] offset:1536
	v_add_u32_e32 v27, 0x41000, v26
	global_load_dwordx4 v[18:21], v27, s[40:41] offset:1536
	v_add_u32_e32 v27, 0x51400, v26
	global_load_dwordx4 v[22:25], v27, s[40:41] offset:1536
	v_cmp_gt_i32_e32 vcc, s14, v78
	v_add_u32_e32 v27, 0x61800, v26
	s_and_b64 exec, exec, vcc
	global_load_dwordx4 v[26:29], v27, s[40:41] offset:1536
	s_or_b64 exec, exec, s[6:7]
	s_branch .Lpf_join
.Lpf_edge:
	v_mov_b32_e32 v26, v78
	s_mov_b32 s6, 0x2aaaaaab
	v_mov_b64_e32 v[6:7], s[18:19]
	v_mul_hi_i32 v0, v26, s6
	v_lshrrev_b32_e32 v2, 31, v0
	v_ashrrev_i32_e32 v0, 2, v0
	v_add_u32_e32 v2, v0, v2
	s_movk_i32 s6, 0xffe8
	v_mad_u64_u32 v[4:5], s[6:7], v2, s6, v[26:27]
	s_ashr_i32 s6, s76, 31
	s_add_u32 s7, s36, s76
	s_addc_u32 s40, s37, s6
	s_add_u32 s6, s7, -2
	v_ashrrev_i32_e32 v3, 31, v2
	s_addc_u32 s7, s40, -1
	v_lshrrev_b32_e32 v0, 3, v4
	v_lshl_add_u64 v[4:5], s[6:7], 0, v[2:3]
	v_mad_u64_u32 v[6:7], s[6:7], v4, s71, v[6:7]
	s_movk_i32 s6, 0x180
	s_nop 0
	v_mul_lo_u32 v4, v0, s6
	v_mad_i32_i24 v7, v5, s71, v7
	v_ashrrev_i32_e32 v5, 31, v4
	v_readlane_b32 s6, v253, 56
	v_lshl_add_u64 v[4:5], v[4:5], 1, v[6:7]
	v_readlane_b32 s7, v253, 57
	v_lshlrev_b32_e32 v0, 4, v26
	v_add3_u32 v27, s76, -2, v2
	v_lshl_add_u64 v[4:5], s[6:7], 1, v[4:5]
	s_movk_i32 s6, 0xf0
	v_and_b32_e32 v0, 0x70, v0
	v_cmp_gt_i32_e64 s[6:7], s6, v26
	v_cmp_gt_u32_e32 vcc, s77, v27
	v_mov_b32_e32 v6, v1
	v_mov_b32_e32 v7, v1
	v_lshl_add_u64 v[8:9], v[4:5], 0, v[0:1]
	s_and_b64 vcc, s[6:7], vcc
	v_mov_b64_e32 v[2:3], v[6:7]
	v_mov_b64_e32 v[4:5], v[6:7]
	s_and_saveexec_b64 s[40:41], vcc
	s_cbranch_execz .LBB0_342
	global_load_dwordx4 v[2:5], v[8:9], off offset:1536

; __device__ void dn_item(const Params& p, int l, int item, char* smem, int wv) {
;     ...
;     if (wave == 0) {
;       int tok = tb + (dir ? 63 - lane : lane);
;       const float* sc = SC + (gbase + tok) * 32 + dir * 12;
;       scb = sc[h];
;       scg = sc[6 + h];
;     }
.Lpf_join:
	s_and_saveexec_b64 s[6:7], s[94:95]
	s_cbranch_execz .LBB0_356
	v_or_b32_e32 v30, s76, v79
	v_ashrrev_i32_e32 v31, 31, v30
	v_lshl_add_u64 v[30:31], s[36:37], 0, v[30:31]
	v_readlane_b32 s36, v253, 49
	v_lshlrev_b64 v[30:31], 7, v[30:31]
	v_readlane_b32 s37, v253, 50
	s_nop 1
	v_lshl_add_u64 v[30:31], s[36:37], 0, v[30:31]
	global_load_dword v182, v[30:31], off
	global_load_dword v183, v[30:31], off offset:24

; __device__ void dn_item(const Params& p, int l, int item, char* smem, int wv) {
;     ...
;     {
;       float* Xw = X + 16 * wave + fr;
;       float la[6][4], ta[4][4];
;       {
;         int bi6 = 0;
; #pragma unroll
;         for (int r = 1; r < 4; ++r)
; #pragma unroll
;           for (int c = 0; c < 3; ++c)
;             if (c < r) {
; #pragma unroll
;               for (int k4 = 0; k4 < 4; ++k4) la[bi6][k4] = -LfT[(16 * c + 4 * k4 + fq) * 68 + 16 * r + fr];
;               ++bi6;
;             }
; #pragma unroll
;         for (int r = 0; r < 4; ++r)
; #pragma unroll
;           for (int k4 = 0; k4 < 4; ++k4) ta[r][k4] = Tinv[(r * 16 + fr) * 16 + 4 * k4 + fq];
;       }
;       int bidx = 0;
; #pragma unroll
;       for (int r = 0; r < 4; ++r) {
;         f32x4 acc;
;         float bv[3][4];
; #pragma unroll
;         for (int j = 0; j < 4; ++j) acc[j] = Xw[(16 * r + fq * 4 + j) * XS];
; #pragma unroll
;         for (int c = 0; c < 3; ++c)
;           if (c < r) {
; #pragma unroll
;             for (int k4 = 0; k4 < 4; ++k4) bv[c][k4] = Xw[(16 * c + 4 * k4 + fq) * XS];
;           }
;         __builtin_amdgcn_sched_barrier(0);
; #pragma unroll
;         for (int c = 0; c < 3; ++c)
;           if (c < r) {
; #pragma unroll
;             for (int k4 = 0; k4 < 4; ++k4) acc = mfma4f(la[bidx][k4], bv[c][k4], acc);
;             ++bidx;
;           }
; #pragma unroll
;         for (int j = 0; j < 4; ++j) Xw[(16 * r + fq * 4 + j) * XS] = acc[j];
;         float bd[4];
; #pragma unroll
;         for (int k4 = 0; k4 < 4; ++k4) bd[k4] = Xw[(16 * r + 4 * k4 + fq) * XS];
;         f32x4 xr = (f32x4){0.f, 0.f, 0.f, 0.f};
; #pragma unroll
;         for (int k4 = 0; k4 < 4; ++k4) xr = mfma4f(ta[r][k4], bd[k4], xr);
; #pragma unroll
;         for (int j = 0; j < 4; ++j) Xw[(16 * r + fq * 4 + j) * XS] = xr[j];
;       }
;     }
;     lds_barrier();
;     {
;       const int v = tid & 63, ib = (tid >> 6) * 16;
;       float xv[16];
; #pragma unroll
;       for (int ii = 0; ii < 16; ++ii) xv[ii] = X[(ib + ii) * XS + v];
;       __builtin_amdgcn_sched_barrier(0);
; #pragma unroll
;       for (int ii = 0; ii < 16; ii += 2) *(unsigned*)(VnT + v * 72 + ib + ii) = pack2(xv[ii], xv[ii + 1]);
;     }
.LBB0_359:
	s_or_b64 exec, exec, s[6:7]
	s_waitcnt lgkmcnt(0)
	s_barrier
	v_readlane_b32 s36, v254, 36
	s_cmp_lt_u32 s43, 4
	v_readlane_b32 s37, v254, 37
	s_cselect_b64 s[6:7], -1, 0
	v_sub_u32_e32 v164, v193, v189
	v_and_b32_e32 v167, 12, v244
	v_sub_u32_e32 v165, v245, v164
	v_mad_u32_u24 v168, v167, 3, v244
	s_xor_b64 vcc, s[36:37], -1
	v_readlane_b32 s36, v254, 3
	ds_read_b32 v139, v165 offset:64
	ds_read_b32 v140, v165 offset:336
	ds_read_b32 v141, v165 offset:608
	ds_read_b32 v142, v165 offset:880
	ds_read_b32 v143, v165 offset:128
	ds_read_b32 v144, v165 offset:400
	ds_read_b32 v145, v165 offset:672
	ds_read_b32 v146, v165 offset:944
	ds_read_b32 v147, v165 offset:192
	ds_read_b32 v148, v165 offset:464
	ds_read_b32 v149, v165 offset:736
	ds_read_b32 v150, v165 offset:1008
	ds_read_b32 v151, v165 offset:4480
	ds_read_b32 v152, v165 offset:4752
	ds_read_b32 v153, v165 offset:5024
	ds_read_b32 v154, v165 offset:5296
	ds_read_b32 v155, v165 offset:4544
	ds_read_b32 v156, v165 offset:4816
	ds_read_b32 v157, v165 offset:5088
	ds_read_b32 v158, v165 offset:5360
	ds_read_b32 v159, v165 offset:8896
	ds_read_b32 v160, v165 offset:9168
	ds_read_b32 v161, v165 offset:9440
	ds_read_b32 v163, v165 offset:9712
	ds_read_b32 v30, v245 offset:27200
	ds_read_b32 v31, v245 offset:27472
	ds_read_b32 v32, v245 offset:27744
	ds_read_b32 v33, v245 offset:28016
	ds_read_b32 v34, v245 offset:31552
	ds_read_b32 v35, v245 offset:31824
	ds_read_b32 v36, v245 offset:32096
	ds_read_b32 v37, v245 offset:32368
	ds_read_b32 v38, v245 offset:35904
	ds_read_b32 v39, v245 offset:36176
	ds_read_b32 v40, v245 offset:36448
	ds_read_b32 v41, v245 offset:36720
	ds_read_b32 v42, v245 offset:40256
	ds_read_b32 v43, v245 offset:40528
	ds_read_b32 v44, v245 offset:40800
	ds_read_b32 v45, v245 offset:41072
	ds_read_b128 v[46:49], v168
	ds_read_b128 v[50:53], v168 offset:1024
	ds_read_b128 v[54:57], v168 offset:2048
	ds_read_b128 v[58:61], v168 offset:3072
	v_lshlrev_b32_e32 v166, 1, v167
	v_sub_u32_e32 v166, v82, v166
	s_waitcnt lgkmcnt(15)
	v_xor_b32_e32 v139, 0x80000000, v139
	v_xor_b32_e32 v140, 0x80000000, v140
	v_xor_b32_e32 v141, 0x80000000, v141
	v_xor_b32_e32 v142, 0x80000000, v142
	v_xor_b32_e32 v143, 0x80000000, v143
	v_xor_b32_e32 v144, 0x80000000, v144
	v_xor_b32_e32 v145, 0x80000000, v145
	v_xor_b32_e32 v146, 0x80000000, v146
	v_xor_b32_e32 v147, 0x80000000, v147
	v_xor_b32_e32 v148, 0x80000000, v148
	v_xor_b32_e32 v149, 0x80000000, v149
	v_xor_b32_e32 v150, 0x80000000, v150
	v_xor_b32_e32 v151, 0x80000000, v151
	v_xor_b32_e32 v152, 0x80000000, v152
	v_xor_b32_e32 v153, 0x80000000, v153
	v_xor_b32_e32 v154, 0x80000000, v154
	v_xor_b32_e32 v155, 0x80000000, v155
	v_xor_b32_e32 v156, 0x80000000, v156
	v_xor_b32_e32 v157, 0x80000000, v157
	v_xor_b32_e32 v158, 0x80000000, v158
	v_xor_b32_e32 v159, 0x80000000, v159
	v_xor_b32_e32 v160, 0x80000000, v160
	v_xor_b32_e32 v161, 0x80000000, v161
	v_xor_b32_e32 v163, 0x80000000, v163
	s_waitcnt lgkmcnt(0)
	s_barrier
	v_mfma_f32_16x16x4_f32 v[62:65], v46, v30, 0
	v_mfma_f32_16x16x4_f32 v[62:65], v47, v31, v[62:65]
	v_mfma_f32_16x16x4_f32 v[62:65], v48, v32, v[62:65]
	v_mfma_f32_16x16x4_f32 v[62:65], v49, v33, v[62:65]
	s_nop 9
	v_mfma_f32_16x16x4_f32 v[34:37], v139, v62, v[34:37]
	v_mfma_f32_16x16x4_f32 v[38:41], v143, v62, v[38:41]
	v_mfma_f32_16x16x4_f32 v[34:37], v140, v63, v[34:37]
	v_mfma_f32_16x16x4_f32 v[42:45], v147, v62, v[42:45]
	v_mfma_f32_16x16x4_f32 v[34:37], v141, v64, v[34:37]
	v_mfma_f32_16x16x4_f32 v[38:41], v144, v63, v[38:41]
	v_mfma_f32_16x16x4_f32 v[34:37], v142, v65, v[34:37]
	v_mfma_f32_16x16x4_f32 v[42:45], v148, v63, v[42:45]
	v_mfma_f32_16x16x4_f32 v[38:41], v145, v64, v[38:41]
	v_mfma_f32_16x16x4_f32 v[42:45], v149, v64, v[42:45]
	v_mfma_f32_16x16x4_f32 v[38:41], v146, v65, v[38:41]
	v_mfma_f32_16x16x4_f32 v[42:45], v150, v65, v[42:45]
	v_cvt_pk_bf16_f32 v170, v62, v63
	v_cvt_pk_bf16_f32 v171, v64, v65
	ds_write_b64 v166, v[170:171]
	s_nop 1
	v_mfma_f32_16x16x4_f32 v[66:69], v50, v34, 0
	v_mfma_f32_16x16x4_f32 v[66:69], v51, v35, v[66:69]
	v_mfma_f32_16x16x4_f32 v[66:69], v52, v36, v[66:69]
	v_mfma_f32_16x16x4_f32 v[66:69], v53, v37, v[66:69]
	s_nop 9
	v_mfma_f32_16x16x4_f32 v[38:41], v151, v66, v[38:41]
	v_mfma_f32_16x16x4_f32 v[42:45], v155, v66, v[42:45]
	v_mfma_f32_16x16x4_f32 v[38:41], v152, v67, v[38:41]
	v_mfma_f32_16x16x4_f32 v[42:45], v156, v67, v[42:45]
	v_mfma_f32_16x16x4_f32 v[38:41], v153, v68, v[38:41]
	v_mfma_f32_16x16x4_f32 v[42:45], v157, v68, v[42:45]
	v_mfma_f32_16x16x4_f32 v[38:41], v154, v69, v[38:41]
	v_mfma_f32_16x16x4_f32 v[42:45], v158, v69, v[42:45]
	v_cvt_pk_bf16_f32 v172, v66, v67
	v_cvt_pk_bf16_f32 v173, v68, v69
	ds_write_b64 v166, v[172:173] offset:32
	s_nop 5
	v_mfma_f32_16x16x4_f32 v[70:73], v54, v38, 0
	v_mfma_f32_16x16x4_f32 v[70:73], v55, v39, v[70:73]
	v_mfma_f32_16x16x4_f32 v[70:73], v56, v40, v[70:73]
	v_mfma_f32_16x16x4_f32 v[70:73], v57, v41, v[70:73]
	s_nop 9
	v_mfma_f32_16x16x4_f32 v[42:45], v159, v70, v[42:45]
	v_mfma_f32_16x16x4_f32 v[42:45], v160, v71, v[42:45]
	v_mfma_f32_16x16x4_f32 v[42:45], v161, v72, v[42:45]
	v_mfma_f32_16x16x4_f32 v[42:45], v163, v73, v[42:45]
	v_cvt_pk_bf16_f32 v174, v70, v71
	v_cvt_pk_bf16_f32 v175, v72, v73
	ds_write_b64 v166, v[174:175] offset:64
	s_nop 6
	v_mfma_f32_16x16x4_f32 v[74:77], v58, v42, 0
	v_mfma_f32_16x16x4_f32 v[74:77], v59, v43, v[74:77]
	v_mfma_f32_16x16x4_f32 v[74:77], v60, v44, v[74:77]
	v_mfma_f32_16x16x4_f32 v[74:77], v61, v45, v[74:77]
	s_nop 9
	v_cvt_pk_bf16_f32 v170, v74, v75
	v_cvt_pk_bf16_f32 v171, v76, v77
	ds_write_b64 v166, v[170:171] offset:96
	s_waitcnt lgkmcnt(0)
	s_barrier
; __device__ __forceinline__ u16 f2bf(float f) { return (u16)(pack2(f, 0.f) & 0xffffu); }
; __device__ void dn_item(const Params& p, int l, int item, char* smem, int wv) {
;     ...
;     {
;       float ge[4];
; #pragma unroll
;       for (int j = 0; j < 4; ++j) ge[j] = gcs[16 * wave + fq * 4 + j];
;       const float glast = gcs[63];
;       if (need_out) {
;         f32x4 oo[4];
; #pragma unroll
;         for (int n = 0; n < 4; ++n) oo[n] = (f32x4){0.f, 0.f, 0.f, 0.f};
;         {
;           bf16x8 qa[2], sbt[2][4];
; #pragma unroll
;           for (int kk = 0; kk < 2; ++kk) {
;             qa[kk] = *(const bf16x8*)(Qb + (16 * wave + fr) * 72 + kk * 32 + fq * 8);
; #pragma unroll
;             for (int n = 0; n < 4; ++n) sbt[kk][n] = *(const bf16x8*)(Stb + (n * 16 + fr) * 72 + kk * 32 + fq * 8);
;           }
;           __builtin_amdgcn_sched_barrier(0);
; #pragma unroll
;           for (int kk = 0; kk < 2; ++kk)
; #pragma unroll
;             for (int n = 0; n < 4; ++n) oo[n] = mfma16(qa[kk], sbt[kk][n], oo[n]);
;         }
;         __builtin_amdgcn_sched_barrier(0);
;         {
;           bf16x8 ia[2], vbt[2][4];
; #pragma unroll
;           for (int kk = 0; kk < 2; ++kk) {
;             ia[kk] = *(const bf16x8*)(Ib + (16 * wave + fr) * 72 + kk * 32 + fq * 8);
; #pragma unroll
;             for (int n = 0; n < 4; ++n) vbt[kk][n] = *(const bf16x8*)(VnT + (n * 16 + fr) * 72 + kk * 32 + fq * 8);
;           }
;           __builtin_amdgcn_sched_barrier(0);
; #pragma unroll
;           for (int j = 0; j < 4; ++j) {
;             float e = __expf(ge[j]);
; #pragma unroll
;             for (int n = 0; n < 4; ++n) oo[n][j] *= e;
;           }
; #pragma unroll
;           for (int kk = 0; kk < 2; ++kk)
; #pragma unroll
;             for (int n = 0; n < 4; ++n) oo[n] = mfma16(ia[kk], vbt[kk][n], oo[n]);
;         }
; #pragma unroll
;         for (int n = 0; n < 4; ++n)
; #pragma unroll
;           for (int j = 0; j < 4; ++j) {
;             int i = 16 * wave + fq * 4 + j;
;             int tok = tb + (dir ? 63 - i : i);
;             Obuf[(gbase + tok) * 384 + h * 64 + n * 16 + fr] = f2bf(oo[n][j]);
;           }
;         __builtin_amdgcn_sched_barrier(0);
	s_and_b64 s[6:7], vcc, s[6:7]
	v_mov_b32_e32 v30, s36
	ds_read_b32 v30, v30
	s_and_b64 vcc, exec, s[6:7]
	s_cbranch_vccnz .Ldn_noout
	v_add_u32_e32 v56, v80, v89
	v_add_u32_e32 v64, v80, v203
	v_add_u32_e32 v68, v80, v204
	v_add_u32_e32 v31, 0x11e40, v193
	ds_read_b32 v31, v31
	ds_read_b128 v[32:35], v82 offset:45632
	ds_read_b32 v118, v210
	ds_read_b64 v[76:77], v205
	ds_read_b128 v[36:39], v0 offset:64064
	ds_read_b128 v[40:43], v82 offset:45696
	ds_read_b128 v[44:47], v56 offset:64064
	ds_read_b128 v[48:51], v0 offset:64128
	ds_read_b128 v[52:55], v64 offset:64064
	ds_read_b128 v[56:59], v56 offset:64128
	ds_read_b128 v[60:63], v68 offset:64064
	ds_read_b128 v[64:67], v64 offset:64128
	ds_read_b128 v[68:71], v68 offset:64128
	s_and_b64 s[6:7], s[44:45], exec
	s_cselect_b32 s36, s43, s42
	s_cselect_b32 s6, 3, 63
	s_sub_i32 s37, s6, s36
	v_readlane_b32 s6, v253, 40
	v_readlane_b32 s7, v253, 41
	s_and_b64 s[6:7], s[6:7], exec
	s_cselect_b32 s36, s36, s37
	s_and_b64 s[6:7], s[44:45], exec
	v_readlane_b32 s40, v253, 51
	v_readlane_b32 s6, v253, 44
	v_readlane_b32 s41, v253, 52
	s_cselect_b32 s7, s6, s41
	v_readlane_b32 s6, v253, 43
	s_cselect_b32 s6, s6, s40
	s_lshl_b32 s40, s36, 6
	s_waitcnt lgkmcnt(8)
	v_mfma_f32_16x16x32_bf16 v[36:39], v[36:39], v[32:35], 0
	s_waitcnt lgkmcnt(6)
	v_mfma_f32_16x16x32_bf16 v[44:47], v[44:47], v[32:35], 0
	s_waitcnt lgkmcnt(4)
	v_mfma_f32_16x16x32_bf16 v[52:55], v[52:55], v[32:35], 0
	s_waitcnt lgkmcnt(2)
	v_mfma_f32_16x16x32_bf16 v[32:35], v[60:63], v[32:35], 0
	v_mfma_f32_16x16x32_bf16 v[36:39], v[48:51], v[40:43], v[36:39]
	v_mfma_f32_16x16x32_bf16 v[44:47], v[56:59], v[40:43], v[44:47]
	s_waitcnt lgkmcnt(1)
	v_mfma_f32_16x16x32_bf16 v[48:51], v[64:67], v[40:43], v[52:55]
	s_waitcnt lgkmcnt(0)
	v_mfma_f32_16x16x32_bf16 v[32:35], v[68:71], v[40:43], v[32:35]
	ds_read_b128 v[40:43], v82 offset:17408
	ds_read_b128 v[52:55], v82 offset:17472
	ds_read_b128 v[56:59], v0
	ds_read_b128 v[60:63], v0 offset:64
	ds_read_b128 v[64:67], v0 offset:2304
	ds_read_b128 v[68:71], v0 offset:2368
	ds_read_b128 v[72:75], v0 offset:4608
	ds_read_b128 v[106:109], v0 offset:4672
	ds_read_b128 v[110:113], v0 offset:6912
	ds_read_b128 v[114:117], v0 offset:6976
	v_mul_f32_e32 v31, 0x3fb8aa3b, v31
	v_exp_f32_e32 v76, v31
	s_nop 0
	v_mov_b32_e32 v77, v76
	v_mov_b32_e32 v118, v76
	v_mov_b32_e32 v119, v76
	s_movk_i32 s41, 0x300
	v_pk_mul_f32 v[36:37], v[76:77], v[36:37]
	v_pk_mul_f32 v[44:45], v[76:77], v[44:45]
	v_pk_mul_f32 v[38:39], v[118:119], v[38:39]
	v_pk_mul_f32 v[46:47], v[118:119], v[46:47]
	v_pk_mul_f32 v[48:49], v[76:77], v[48:49]
	v_pk_mul_f32 v[50:51], v[118:119], v[50:51]
	s_waitcnt lgkmcnt(7)
	v_mfma_f32_16x16x32_bf16 v[36:39], v[56:59], v[40:43], v[36:39]
	v_mul_f32_e64 v32, v76, v32
	v_mul_f32_e64 v33, v77, v33
	v_pk_mul_f32 v[34:35], v[118:119], v[34:35]
	s_waitcnt lgkmcnt(5)
	v_mfma_f32_16x16x32_bf16 v[44:47], v[64:67], v[40:43], v[44:47]
	s_waitcnt lgkmcnt(3)
	v_mfma_f32_16x16x32_bf16 v[48:51], v[72:75], v[40:43], v[48:51]
	s_waitcnt lgkmcnt(1)
	v_mfma_f32_16x16x32_bf16 v[32:35], v[110:113], v[40:43], v[32:35]
	v_mfma_f32_16x16x32_bf16 v[36:39], v[60:63], v[52:55], v[36:39]
	v_mfma_f32_16x16x32_bf16 v[40:43], v[68:71], v[52:55], v[44:47]
	v_mfma_f32_16x16x32_bf16 v[44:47], v[106:109], v[52:55], v[48:51]
	s_waitcnt lgkmcnt(0)
	v_mfma_f32_16x16x32_bf16 v[32:35], v[114:117], v[52:55], v[32:35]
	v_add_u32_e32 v48, -16, v193
	v_readlane_b32 s36, v253, 40
	v_readlane_b32 s37, v253, 41
	v_lshrrev_b32_e32 v48, 2, v48
	v_sub_u32_e32 v49, 63, v48
	v_and_b32_e32 v50, 12, v244
	v_cndmask_b32_e64 v48, v49, v48, s[36:37]
	v_readlane_b32 s36, v253, 58
	v_readlane_b32 s37, v253, 59
	v_add_u32_e32 v48, s40, v48
	v_lshlrev_b32_e32 v50, 1, v50
	v_ashrrev_i32_e32 v49, 31, v48
	v_mov_b32_e32 v51, v1
	v_lshl_add_u64 v[48:49], s[6:7], 0, v[48:49]
	v_lshl_add_u64 v[50:51], s[36:37], 0, v[50:51]
	v_mad_u64_u32 v[50:51], s[36:37], v48, s41, v[50:51]
	v_mad_i32_i24 v51, v49, s41, v51
	v_cvt_pk_bf16_f32 v52, v36, v37
	v_cvt_pk_bf16_f32 v53, v38, v39
	global_store_dwordx2 v[50:51], v[52:53], off
	v_cvt_pk_bf16_f32 v54, v40, v41
	v_cvt_pk_bf16_f32 v55, v42, v43
	global_store_dwordx2 v[50:51], v[54:55], off offset:32
	v_cvt_pk_bf16_f32 v56, v44, v45
	v_cvt_pk_bf16_f32 v57, v46, v47
	global_store_dwordx2 v[50:51], v[56:57], off offset:64
	v_cvt_pk_bf16_f32 v58, v32, v33
	v_cvt_pk_bf16_f32 v59, v34, v35
	global_store_dwordx2 v[50:51], v[58:59], off offset:96
; __device__ __forceinline__ u16 f2bf(float f) { return (u16)(pack2(f, 0.f) & 0xffffu); }
; __device__ void dn_item(const Params& p, int l, int item, char* smem, int wv) {
;     ...
;   auto commit = [&]() {
;     int tl = tid;
;     asm volatile("" : "+v"(tl));
;     const int rr = tl / 24, seg = tl - rr * 24, part = seg >> 3, s8 = seg & 7;
; #pragma unroll
;     for (int q = 0; q < 7; ++q) {
;       int r = rr + 10 * q;
;       if (tl < 240 && r < 68) *(uint4*)(R0 + r * RS + part * 64 + s8 * 8) = pre[q];
;     ...
;       for (int n = 0; n < 4; ++n)
; #pragma unroll
;         for (int j = 0; j < 4; ++j) S[n][j] = S[n][j] * dec + dS[n][j];
;     }
;     lds_barrier();
; #pragma unroll
;     for (int n = 0; n < 4; ++n)
; #pragma unroll
;       for (int j = 0; j < 4; ++j) Stb[(16 * wave + fq * 4 + j) * 72 + n * 16 + fr] = f2bf(S[n][j]);
;     if (step + 1 < 68) commit();
.LBB0_361:
	ds_read_b128 v[32:35], v82
	ds_read_b128 v[36:39], v82 offset:64
	ds_read_b128 v[40:43], v0 offset:54848
	ds_read_b128 v[44:47], v0 offset:54912
	ds_read_b128 v[48:51], v0 offset:57152
	ds_read_b128 v[52:55], v0 offset:57216
	ds_read_b128 v[56:59], v0 offset:59456
	ds_read_b128 v[60:63], v0 offset:59520
	ds_read_b128 v[64:67], v0 offset:61760
	ds_read_b128 v[68:71], v0 offset:61824
	s_waitcnt lgkmcnt(7)
	v_mfma_f32_16x16x32_bf16 v[40:43], v[40:43], v[32:35], 0
	v_mul_f32_e32 v0, 0x3fb8aa3b, v30
	v_exp_f32_e32 v0, v0
	s_waitcnt lgkmcnt(0)
	s_waitcnt lgkmcnt(5)
	v_mfma_f32_16x16x32_bf16 v[48:51], v[48:51], v[32:35], 0
	s_barrier
	s_andn2_b64 vcc, exec, s[38:39]
	s_waitcnt lgkmcnt(3)
	v_mfma_f32_16x16x32_bf16 v[56:59], v[56:59], v[32:35], 0
	s_waitcnt lgkmcnt(1)
	v_mfma_f32_16x16x32_bf16 v[32:35], v[64:67], v[32:35], 0
	v_mfma_f32_16x16x32_bf16 v[40:43], v[44:47], v[36:39], v[40:43]
	v_mfma_f32_16x16x32_bf16 v[44:47], v[52:55], v[36:39], v[48:51]
	s_waitcnt lgkmcnt(0)
	v_mfma_f32_16x16x32_bf16 v[30:33], v[68:71], v[36:39], v[32:35]
	s_nop 4
	v_fma_f32 v90, v90, v0, v40
	v_fma_f32 v91, v91, v0, v41
	v_pk_fma_f32 v[92:93], v[92:93], v[0:1], v[42:43] op_sel_hi:[1,0,1]
	v_pk_fma_f32 v[94:95], v[94:95], v[0:1], v[44:45] op_sel_hi:[1,0,1]
	v_mfma_f32_16x16x32_bf16 v[40:43], v[60:63], v[36:39], v[56:59]
	v_fma_f32 v96, v96, v0, v46
	v_fma_f32 v97, v97, v0, v47
	v_pk_fma_f32 v[102:103], v[102:103], v[0:1], v[30:31] op_sel_hi:[1,0,1]
	v_pk_fma_f32 v[104:105], v[104:105], v[0:1], v[32:33] op_sel_hi:[1,0,1]
	s_nop 3
	v_pk_fma_f32 v[98:99], v[98:99], v[0:1], v[40:41] op_sel_hi:[1,0,1]
	v_pk_fma_f32 v[100:101], v[100:101], v[0:1], v[42:43] op_sel_hi:[1,0,1]
	v_cvt_pk_bf16_f32 v144, v90, v91
	v_cvt_pk_bf16_f32 v145, v92, v93
	ds_write_b64 v166, v[144:145] offset:64064
	v_cvt_pk_bf16_f32 v146, v94, v95
	v_cvt_pk_bf16_f32 v147, v96, v97
	ds_write_b64 v166, v[146:147] offset:64096
	v_cvt_pk_bf16_f32 v148, v98, v99
	v_cvt_pk_bf16_f32 v149, v100, v101
	ds_write_b64 v166, v[148:149] offset:64128
	v_cvt_pk_bf16_f32 v150, v102, v103
	v_cvt_pk_bf16_f32 v151, v104, v105
	ds_write_b64 v166, v[150:151] offset:64160
	s_cbranch_vccnz .LBB0_338
	s_movk_i32 s6, 0xf0
	v_cmp_gt_i32_e32 vcc, s6, v78
	s_and_saveexec_b64 s[6:7], vcc
	s_cbranch_execz .LBB0_365
	s_waitcnt vmcnt(4)
	ds_write_b128 v200, v[2:5]
	ds_write_b128 v200, v[6:9] offset:4000
	ds_write_b128 v200, v[10:13] offset:8000
	ds_write_b128 v200, v[14:17] offset:12000
	ds_write_b128 v200, v[18:21] offset:16000
	ds_write_b128 v200, v[22:25] offset:20000
	s_or_b64 exec, exec, s[6:7]
	v_cmp_gt_i32_e32 vcc, s14, v78
	s_and_saveexec_b64 s[6:7], vcc
	s_cbranch_execnz .LBB0_366

; __device__ __forceinline__ float sigmoidf_(float x) { return __builtin_amdgcn_rcpf(1.f + __expf(-x)); }
; __device__ void dn_item(const Params& p, int l, int item, char* smem, int wv) {
;     ...
;   auto commit = [&]() {
;     int tl = tid;
;     asm volatile("" : "+v"(tl));
;     const int rr = tl / 24, seg = tl - rr * 24, part = seg >> 3, s8 = seg & 7;
; #pragma unroll
;     for (int q = 0; q < 7; ++q) {
;       int r = rr + 10 * q;
;       if (tl < 240 && r < 68) *(uint4*)(R0 + r * RS + part * 64 + s8 * 8) = pre[q];
;     }
;     if (wave == 0) {
;       float bet = sigmoidf_(scb);
;       float xx = scg + dtb;
;       float ex = __expf(xx);
;       float sp = xx > 20.f ? xx : (ex < 0.01f ? ex * (1.f - ex * (0.5f - ex * (1.f / 3.f))) : __logf(1.f + ex));
;       float g = -aexp * sp;
.LBB0_365:
	s_or_b64 exec, exec, s[6:7]
	v_cmp_gt_i32_e32 vcc, s14, v78
	s_and_saveexec_b64 s[6:7], vcc
	s_cbranch_execz .LBB0_364
.LBB0_366:
	s_waitcnt vmcnt(4)
	ds_write_b128 v200, v[26:29] offset:24000
	s_or_b64 exec, exec, s[6:7]
	s_and_saveexec_b64 s[36:37], s[94:95]
	s_cbranch_execz .LBB0_337
.LBB0_367:
	s_waitcnt vmcnt(4)
	v_add_f32_e32 v0, v81, v183
	s_mov_b32 s6, 0x41a00000
	v_cmp_nlt_f32_e32 vcc, s6, v0
	s_and_saveexec_b64 s[38:39], vcc
	s_cbranch_execz .LBB0_336
	v_mul_f32_e32 v0, 0x3fb8aa3b, v0
	v_exp_f32_e32 v30, v0
	s_mov_b32 s6, 0x3c23d70a
	v_cmp_ngt_f32_e32 vcc, s6, v30
	s_and_saveexec_b64 s[6:7], vcc
	s_xor_b64 s[44:45], exec, s[6:7]
	s_cbranch_execz .LBB0_370
	v_add_f32_e32 v0, 1.0, v30
	v_cmp_gt_f32_e32 vcc, s15, v0
	s_mov_b32 s6, 0x3f317217
	s_nop 0
	v_cndmask_b32_e64 v30, 0, 32, vcc
	v_ldexp_f32 v0, v0, v30
	v_log_f32_e32 v0, v0
	s_nop 0
	v_mul_f32_e32 v30, 0x3f317217, v0
	v_fma_f32 v30, v0, s6, -v30
	v_fmac_f32_e32 v30, 0x3377d1cf, v0
	s_mov_b32 s6, 0x7f800000
	v_fmac_f32_e32 v30, 0x3f317217, v0
	v_cmp_lt_f32_e64 s[6:7], |v0|, s6
	s_nop 1
	v_cndmask_b32_e64 v0, v0, v30, s[6:7]
	v_mov_b32_e32 v30, 0x41b17218
	v_cndmask_b32_e32 v30, 0, v30, vcc
	v_sub_f32_e32 v0, v0, v30
